# static s_setprio 1 for waves 0-3 during the retention+attention phase (both halves run the same program in lockstep), reset to 0 at the next phase
# speedup vs baseline: 1.0057x; 1.0057x over previous
; DI void grid_barrier(unsigned* bar, unsigned& nbar, const bool hier, const unsigned xcd, const unsigned per_xcd) {
;     ...
;     __syncthreads();
;     ++nbar;
; __global__ void __launch_bounds__(512, 2) mega(Params p) {
;     ...
;         if (3 > p.ph_lo) grid_barrier(bar, nbar, hier, my_xcd, (unsigned)G / 8u);
;     ...
;             phase_retention(p, lds, c_eff); __syncthreads();
;     ...
;             phase_attention(p, lds);
.LBB0_198:
	s_or_b64 exec, exec, s[0:1]
	s_barrier
	v_readfirstlane_b32 s98, v0
	s_nop 3
	s_and_b32 s98, s98, 0x3ff
	s_lshr_b32 s98, s98, 6
	s_cmp_ge_u32 s98, 4
	s_cbranch_scc1 .Lprio_skip_ret
	s_setprio 1
